# attention chunk loop: invariant exchange addresses hoisted out of the loop; key chunks >= 5 chunks back read the single clamped relative-position bias entry instead of 16 index computations + 16 LDS g
# speedup vs baseline: 1.0058x; 1.0007x over previous
; #define LAS __attribute__((address_space(3)))
; __device__ __forceinline__ void lds_barrier() { asm volatile("s_waitcnt lgkmcnt(0)" ::: "memory"); __builtin_amdgcn_s_barrier(); asm volatile("" ::: "memory"); }
; __device__ __forceinline__ int opaque_tid() { int t = threadIdx.x; asm volatile("" : "+v"(t)); return t; }
; #define ATT_LOAD(jj_) do { const bf16_t* kb_ = zb + (size_t)((c - 8 + (jj_)) * 64 + skey) * ZLD + hp * 128 + spc * 8; \
;         kr[0] = *(const u32x4*)(kb_ + 256); vr[0] = *(const u32x4*)(kb_ + 512); kr[1] = *(const u32x4*)(kb_ + (size_t)32 * ZLD + 256); vr[1] = *(const u32x4*)(kb_ + (size_t)32 * ZLD + 512); } while (0)
; __device__ __forceinline__ void attn_item(const Params& p, int l, int item, LAS unsigned char* lds) {
;     const int tid = opaque_tid(), wid = tid >> 6, lane = tid & 63, fr = lane & 15, fq = lane >> 4;
;     const int b = item >> 6, c = (item >> 1) & 31, hp = item & 1;
;     const int hh = wid >> 2, head = hp * 2 + hh, q0 = (wid & 3) * 16;
;     constexpr int KST = 272, VST = 288, KBUF = 64 * KST, BUFB = KBUF + 64 * VST;
;     LAS float* bias_s = (LAS float*)(lds + 2 * BUFB);
;     const bf16_t* zb = p.z + (size_t)b * SEQ * ZLD;
;     lds_barrier();
;     for (int i = tid; i < 640; i += 512) { const int h2 = i / 320, idx = i - h2 * 320; bias_s[i] = p.rel_bias[((size_t)l * 4 + hp * 2 + h2) * 320 + idx] * LOG2E; }
;     const bf16_t* qp = zb + (size_t)(c * 64 + q0 + fr) * ZLD + head * 64 + fq * 8;
;     const bf16x8 qf0 = *(const bf16x8*)qp, qf1 = *(const bf16x8*)(qp + 32);
;     f32x4 o[4];
; #pragma unroll
;     for (int dt = 0; dt < 4; ++dt) o[dt] = ZERO4;
;     float mrun = -1e30f, lsum = 0.f;
;     const int jj0 = c >= 8 ? 0 : 8 - c;
;     const int skey = tid >> 4, spc = tid & 15;
;     u32x4 kr[2], vr[2];
;     ...
;     ATT_LOAD(jj0);
;     ...
;         cmax = fmaxf(cmax, __shfl_xor(cmax, 16)); cmax = fmaxf(cmax, __shfl_xor(cmax, 32));
.LBB0_409:
	s_or_b64 exec, exec, s[4:5]
	s_add_i32 s4, s69, 0xffffff00
	s_ashr_i32 s4, s4, 6
	s_bfe_u32 s22, s42, 0x50001
	v_lshrrev_b32_e32 v0, 2, v28
	s_ashr_i32 s5, s4, 31
	s_mul_i32 s7, s4, 0xb00000
	v_and_b32_e32 v3, 15, v28
	v_and_b32_e32 v58, 48, v0
	s_mul_hi_i32 s6, s4, 0xb00000
	s_add_u32 s16, s8, s7
	s_addc_u32 s17, s9, s6
	s_lshl_b32 s6, s22, 6
	v_or_b32_e32 v31, v58, v3
	s_sub_i32 s7, 8, s22
	v_or_b32_e32 v0, s6, v31
	s_cmp_lt_u32 s22, 8
	v_mul_u32_u24_e32 v0, 0xb00, v0
	s_cselect_b32 s7, s7, 0
	v_ashrrev_i32_e32 v30, 8, v28
	v_lshlrev_b32_e32 v0, 1, v0
	v_mov_b32_e32 v1, v2
	s_add_i32 s22, s22, s7
	v_lshl_add_u64 v[4:5], s[16:17], 0, v[0:1]
	v_add_lshl_u32 v0, v30, s15, 6
	s_lshl_b32 s15, s22, 6
	v_ashrrev_i32_e32 v32, 4, v28
	s_addk_i32 s15, 0xfe00
	v_add_u32_e32 v14, s15, v32
	v_mov_b64_e32 v[12:13], s[16:17]
	s_movk_i32 s22, 0x1600
	v_mad_i64_i32 v[12:13], s[16:17], v14, s22, v[12:13]
	s_mov_b32 s15, s43
	s_lshl_b32 s14, s14, 8
	v_lshl_add_u64 v[12:13], v[12:13], 0, s[14:15]
	v_lshlrev_b32_e32 v54, 4, v3
	v_mov_b32_e32 v55, v2
	v_bfe_u32 v29, v28, 4, 2
	v_ashrrev_i32_e32 v1, 31, v0
	v_lshl_add_u64 v[20:21], v[12:13], 0, v[54:55]
	s_mov_b32 s14, 0x2c000
	v_lshl_add_u64 v[4:5], v[0:1], 1, v[4:5]
	v_lshlrev_b32_e32 v52, 4, v29
	v_mov_b32_e32 v53, v2
	v_add_co_u32_e32 v24, vcc, s14, v20
	v_lshl_add_u64 v[8:9], v[4:5], 0, v[52:53]
	s_nop 0
	v_addc_co_u32_e32 v25, vcc, 0, v21, vcc
	global_load_dwordx4 v[4:7], v[8:9], off
	s_nop 0
	global_load_dwordx4 v[8:11], v[8:9], off offset:64
	s_nop 0
	global_load_dwordx4 v[12:15], v[20:21], off offset:512
	global_load_dwordx4 v[16:19], v[20:21], off offset:1024
	s_nop 0
	global_load_dwordx4 v[20:23], v[24:25], off offset:512
	s_nop 0
	global_load_dwordx4 v[24:27], v[24:25], off offset:1024
	s_movk_i32 s15, 0x110
	v_mul_lo_u32 v55, v32, s15
	s_movk_i32 s15, 0x120
	v_mul_lo_u32 v60, v32, s15
	v_readlane_b32 s15, v255, 10
	v_lshlrev_b32_e32 v53, 2, v29
	v_bfe_u32 v29, v28, 2, 2
	v_mov_b32_e32 v33, s15
	s_add_i32 s15, s39, s95
	s_add_i32 s15, s15, s96
	s_bfe_u32 s15, s15, 0x50001
	v_lshlrev_b32_e32 v28, 3, v28
	s_add_i32 s15, s7, s15
	v_and_b32_e32 v64, 24, v28
	v_lshl_add_u32 v28, s15, 6, v32
	v_or_b32_e32 v29, v53, v29
	v_add_u32_e32 v28, 0xfffffe40, v28
	v_mul_u32_u24_e32 v66, 0x120, v29
	v_mad_i64_i32 v[28:29], s[16:17], v28, s22, 0
	v_mad_i64_i32 v[28:29], s[16:17], s4, v212, v[28:29]
	s_and_b32 s0, s0, 0x100
	v_or3_b32 v28, v28, s0, v54
	v_lshl_add_u64 v[28:29], s[8:9], 0, v[28:29]
	s_mov_b64 s[16:17], 0x2c400
	v_lshl_add_u64 v[56:57], v[28:29], 0, s[16:17]
	v_sub_u32_e32 v28, v31, v53
	s_lshl_b32 s0, s7, 6
	v_mov_b32_e32 v68, 0
	s_mov_b32 s14, 0
	v_add_u32_e32 v59, 0x2200, v55
	v_add_u32_e32 v61, 0x2400, v60
	v_lshlrev_b32_e32 v62, 7, v30
	v_mad_i32_i24 v63, v30, s31, v33
	v_mul_u32_u24_e32 v65, 0x110, v3
	v_subrev_u32_e32 v67, s0, v28
	s_addk_i32 s0, 0xfe00
	v_mov_b32_e32 v70, 0xf149f2ca
	v_mov_b32_e32 v28, 0
	v_mov_b32_e32 v29, v68
	v_mov_b32_e32 v30, v68
	v_mov_b32_e32 v31, v68
	v_mov_b32_e32 v32, 0
	v_mov_b32_e32 v33, v68
	v_mov_b32_e32 v34, v68
	v_mov_b32_e32 v35, v68
	v_mov_b32_e32 v36, 0
	v_mov_b32_e32 v37, v68
	v_mov_b32_e32 v38, v68
	v_mov_b32_e32 v39, v68
	v_mov_b32_e32 v40, 0
	v_mov_b32_e32 v41, v68
	v_mov_b32_e32 v42, v68
	v_mov_b32_e32 v43, v68
	v_and_b32_e32 v47, 64, v207
	v_xor_b32_e32 v45, 16, v207
	v_add_u32_e32 v47, 64, v47
	v_cmp_lt_i32_e32 vcc, v45, v47
	v_xor_b32_e32 v46, 32, v207
	s_nop 1
	v_cndmask_b32_e32 v45, v207, v45, vcc
	v_cmp_lt_i32_e32 vcc, v46, v47
	v_lshlrev_b32_e32 v45, 2, v45
	s_nop 1
	v_cndmask_b32_e32 v46, v207, v46, vcc
	v_lshlrev_b32_e32 v46, 2, v46

; #define LAS __attribute__((address_space(3)))
; __device__ __forceinline__ f32x4 mfma16(bf16x8 a, bf16x8 b, f32x4 c) { return __builtin_amdgcn_mfma_f32_16x16x32_bf16(a, b, c, 0, 0, 0); }
; __device__ __forceinline__ void lds_barrier() { asm volatile("s_waitcnt lgkmcnt(0)" ::: "memory"); __builtin_amdgcn_s_barrier(); asm volatile("" ::: "memory"); }
; #define ATT_LOAD(jj_) do { const bf16_t* kb_ = zb + (size_t)((c - 8 + (jj_)) * 64 + skey) * ZLD + hp * 128 + spc * 8; \
;         kr[0] = *(const u32x4*)(kb_ + 256); vr[0] = *(const u32x4*)(kb_ + 512); kr[1] = *(const u32x4*)(kb_ + (size_t)32 * ZLD + 256); vr[1] = *(const u32x4*)(kb_ + (size_t)32 * ZLD + 512); } while (0)
; __device__ __forceinline__ void attn_item(const Params& p, int l, int item, LAS unsigned char* lds) {
;     ...
;     for (int jj = jj0; jj <= 8; ++jj) {
;         LAS unsigned char* Kb = lds + (jj & 1) * BUFB; LAS unsigned char* Vb = Kb + KBUF;
;         *(LAS u32x4*)(Kb + skey * KST + spc * 16) = kr[0]; *(LAS u32x4*)(Kb + (skey + 32) * KST + spc * 16) = kr[1];
;         *(LAS u32x4*)(Vb + skey * VST + spc * 16) = vr[0]; *(LAS u32x4*)(Vb + (skey + 32) * VST + spc * 16) = vr[1];
;         if (jj < 8) ATT_LOAD(jj + 1);
;         lds_barrier();
;         f32x4 s[4];
; #pragma unroll
;         for (int kt = 0; kt < 4; ++kt) { const LAS unsigned char* kp = Kb + (kt * 16 + fr) * KST + hh * 128 + fq * 16;
;             s[kt] = mfma16(*(const LAS bf16x8*)kp, qf0, ZERO4); s[kt] = mfma16(*(const LAS bf16x8*)(kp + 64), qf1, s[kt]); }
;         const int base = (8 - jj) * 64 + q0 + fr;
;         float cmax = -1e30f;
; #pragma unroll
;         for (int kt = 0; kt < 4; ++kt)
; #pragma unroll
;             for (int j = 0; j < 4; ++j) { const int dist = base - (kt * 16 + fq * 4 + j); const int idx = (dist < 256 ? dist : 256) + 63;
;                 const float sv = s[kt][j] * (0.125f * LOG2E) + bias_s[hh * 320 + idx]; s[kt][j] = sv; cmax = fmaxf(cmax, sv); }
;         cmax = fmaxf(cmax, __shfl_xor(cmax, 16)); cmax = fmaxf(cmax, __shfl_xor(cmax, 32));
.LBB0_412:
	v_add_u32_e32 v69, s15, v62
	v_add3_u32 v87, v69, v52, v65
	v_add3_u32 v69, v69, v64, v66
	v_add_u32_e32 v71, s14, v67
	s_sub_i32 s14, s14, 64
	s_cmp_lt_u32 s7, 4
	s_cbranch_scc1 .Lattn_far_a
	v_add_u32_e32 v88, 0x200, v71
	v_min_i32_e32 v88, 0x100, v88
	v_lshl_add_u32 v88, v88, 2, v63
	v_add_u32_e32 v89, 0x1ff, v71
	v_min_i32_e32 v89, 0x100, v89
	v_lshl_add_u32 v89, v89, 2, v63
	v_add_u32_e32 v90, 0x1fe, v71
	v_min_i32_e32 v90, 0x100, v90
	v_lshl_add_u32 v90, v90, 2, v63
	v_add_u32_e32 v91, 0x1fd, v71
	v_min_i32_e32 v91, 0x100, v91
	v_lshl_add_u32 v91, v91, 2, v63
	v_add_u32_e32 v92, 0x1f0, v71
	v_min_i32_e32 v92, 0x100, v92
	v_lshl_add_u32 v92, v92, 2, v63
	v_add_u32_e32 v93, 0x1ef, v71
	v_min_i32_e32 v93, 0x100, v93
	v_lshl_add_u32 v93, v93, 2, v63
	v_add_u32_e32 v94, 0x1ee, v71
	v_min_i32_e32 v94, 0x100, v94
	v_lshl_add_u32 v94, v94, 2, v63
	v_add_u32_e32 v95, 0x1ed, v71
	v_min_i32_e32 v95, 0x100, v95
	v_lshl_add_u32 v95, v95, 2, v63
	v_add_u32_e32 v96, 0x1e0, v71
	v_min_i32_e32 v96, 0x100, v96
	v_lshl_add_u32 v96, v96, 2, v63
	v_add_u32_e32 v97, 0x1df, v71
	v_min_i32_e32 v97, 0x100, v97
	v_lshl_add_u32 v97, v97, 2, v63
	v_add_u32_e32 v98, 0x1de, v71
	v_min_i32_e32 v98, 0x100, v98
	v_lshl_add_u32 v98, v98, 2, v63
	v_add_u32_e32 v99, 0x1dd, v71
	v_min_i32_e32 v99, 0x100, v99
	v_lshl_add_u32 v99, v99, 2, v63
	v_add_u32_e32 v100, 0x1d0, v71
	v_min_i32_e32 v100, 0x100, v100
	v_lshl_add_u32 v100, v100, 2, v63
	v_add_u32_e32 v101, 0x1cf, v71
	v_min_i32_e32 v101, 0x100, v101
	v_lshl_add_u32 v101, v101, 2, v63
	v_add_u32_e32 v102, 0x1ce, v71
	v_min_i32_e32 v102, 0x100, v102
	v_lshl_add_u32 v102, v102, 2, v63
	v_add_u32_e32 v103, 0x1cd, v71
	v_min_i32_e32 v103, 0x100, v103
	v_lshl_add_u32 v103, v103, 2, v63
.Lattn_far_a:
	s_mov_b64 s[16:17], 0x58000
	v_lshl_add_u64 v[56:57], v[56:57], 0, s[16:17]
	s_waitcnt lgkmcnt(0)
	s_barrier
	s_cmp_lt_u32 s7, 4
	s_cbranch_scc1 .Lattn_far_b
	ds_read_b32 v88, v88 offset:252
	ds_read_b32 v89, v89 offset:252
	ds_read_b32 v90, v90 offset:252
	ds_read_b32 v91, v91 offset:252
	ds_read_b32 v92, v92 offset:252
	ds_read_b32 v93, v93 offset:252
	ds_read_b32 v94, v94 offset:252
	ds_read_b32 v95, v95 offset:252
	ds_read_b32 v96, v96 offset:252
	ds_read_b32 v97, v97 offset:252
	ds_read_b32 v98, v98 offset:252
	ds_read_b32 v99, v99 offset:252
	ds_read_b32 v100, v100 offset:252
	ds_read_b32 v101, v101 offset:252
	ds_read_b32 v102, v102 offset:252
	ds_read_b32 v103, v103 offset:252
.Lattn_join_b:
	ds_read_b128 v[104:107], v87 offset:0
	ds_read_b128 v[108:111], v87 offset:64
	ds_read_b128 v[112:115], v87 offset:4352
	ds_read_b128 v[116:119], v87 offset:4416
	ds_read_b128 v[120:123], v87 offset:8704
	ds_read_b128 v[124:127], v87 offset:8768
	ds_read_b128 v[128:131], v87 offset:13056
	ds_read_b128 v[132:135], v87 offset:13120
	s_mov_b32 s15, 0xf149f2ca
	s_waitcnt lgkmcnt(7)
	v_mfma_f32_16x16x32_bf16 v[180:183], v[104:107], v[4:7], 0
	s_waitcnt lgkmcnt(6)
	v_mfma_f32_16x16x32_bf16 v[72:75], v[108:111], v[8:11], v[180:183]
	ds_read_b64_tr_b16 v[148:149], v69 offset:17408
	ds_read_b64_tr_b16 v[150:151], v69 offset:22016
	ds_read_b64_tr_b16 v[152:153], v69 offset:17440
	ds_read_b64_tr_b16 v[154:155], v69 offset:22048
	ds_read_b64_tr_b16 v[156:157], v69 offset:17472
	ds_read_b64_tr_b16 v[158:159], v69 offset:22080
	ds_read_b64_tr_b16 v[160:161], v69 offset:17504
	ds_read_b64_tr_b16 v[162:163], v69 offset:22112
	s_waitcnt lgkmcnt(13)
	v_mfma_f32_16x16x32_bf16 v[184:187], v[112:115], v[4:7], 0
	s_waitcnt lgkmcnt(12)
	v_mfma_f32_16x16x32_bf16 v[76:79], v[116:119], v[8:11], v[184:187]
	s_waitcnt lgkmcnt(11)
	v_mfma_f32_16x16x32_bf16 v[188:191], v[120:123], v[4:7], 0
	s_waitcnt lgkmcnt(10)
	v_mfma_f32_16x16x32_bf16 v[48:51], v[124:127], v[8:11], v[188:191]
	s_waitcnt lgkmcnt(9)
	v_mfma_f32_16x16x32_bf16 v[192:195], v[128:131], v[4:7], 0
	s_waitcnt lgkmcnt(8)
	v_mfma_f32_16x16x32_bf16 v[80:83], v[132:135], v[8:11], v[192:195]
	s_cmp_lt_u32 s7, 4
	s_cbranch_scc0 .Lattn_near_c
	v_mov_b32_e32 v89, v88
	v_mov_b32_e32 v90, v88
	v_mov_b32_e32 v91, v88
	v_mov_b32_e32 v92, v88
	v_mov_b32_e32 v93, v88
	v_mov_b32_e32 v94, v88
	v_mov_b32_e32 v95, v88
	v_mov_b32_e32 v96, v88
	v_mov_b32_e32 v97, v88
	v_mov_b32_e32 v98, v88
	v_mov_b32_e32 v99, v88
	v_mov_b32_e32 v100, v88
	v_mov_b32_e32 v101, v88
	v_mov_b32_e32 v102, v88
	v_mov_b32_e32 v103, v88
; #define LAS __attribute__((address_space(3)))
; __device__ __forceinline__ unsigned pk2s(float lo, float hi) { unsigned r; asm("s_nop 0\n\tv_cvt_pk_bf16_f32 %0, %1, %2" : "=v"(r) : "v"(lo), "v"(hi)); return r; }
; __device__ __forceinline__ float fexp2(float x) { return __builtin_amdgcn_exp2f(x); }
; __device__ __forceinline__ f32x4 mfma16(bf16x8 a, bf16x8 b, f32x4 c) { return __builtin_amdgcn_mfma_f32_16x16x32_bf16(a, b, c, 0, 0, 0); }
; __device__ __forceinline__ void attn_item(const Params& p, int l, int item, LAS unsigned char* lds) {
;     ...
;             for (int j = 0; j < 4; ++j) { const int dist = base - (kt * 16 + fq * 4 + j); const int idx = (dist < 256 ? dist : 256) + 63;
;                 const float sv = s[kt][j] * (0.125f * LOG2E) + bias_s[hh * 320 + idx]; s[kt][j] = sv; cmax = fmaxf(cmax, sv); }
;         cmax = fmaxf(cmax, __shfl_xor(cmax, 16)); cmax = fmaxf(cmax, __shfl_xor(cmax, 32));
;         const float mnew = fmaxf(mrun, cmax), alpha = fexp2(mrun - mnew); mrun = mnew;
;         float ps = 0.f;
; #pragma unroll
;         for (int kt = 0; kt < 4; ++kt)
; #pragma unroll
;             for (int j = 0; j < 4; ++j) { const float e = fexp2(s[kt][j] - mnew); s[kt][j] = e; ps += e; }
;         lsum = lsum * alpha + ps;
; #pragma unroll
;         for (int dt = 0; dt < 4; ++dt) o[dt] *= alpha;
; #pragma unroll
;         for (int i = 0; i < 2; ++i) {
;             u32x4 pw; pw.x = pk2s(s[2 * i][0], s[2 * i][1]); pw.y = pk2s(s[2 * i][2], s[2 * i][3]); pw.z = pk2s(s[2 * i + 1][0], s[2 * i + 1][1]); pw.w = pk2s(s[2 * i + 1][2], s[2 * i + 1][3]);
;             const bf16x8 pb = as_bf8(pw);
;             const LAS unsigned char* vp = Vb + (32 * i + 4 * fq + (fr >> 2)) * VST + hh * 128 + (fr & 3) * 8;
; #pragma unroll
;             for (int dt = 0; dt < 4; ++dt) {
;                 const v4i16_t a0 = __builtin_amdgcn_ds_read_tr16_b64_v4i16((LAS v4i16_t*)(vp + dt * 32));
;                 const v4i16_t a1 = __builtin_amdgcn_ds_read_tr16_b64_v4i16((LAS v4i16_t*)(vp + 16 * VST + dt * 32));
;                 const bf16x8 av = __builtin_shufflevector(a0, a1, 0, 1, 2, 3, 4, 5, 6, 7);
;                 o[dt] = mfma16(av, pb, o[dt]); }
;         }
;     }
.Lattn_near_c:
	v_fmac_f32_e32 v88, 0x3e38aa3b, v72
	v_fmac_f32_e32 v89, 0x3e38aa3b, v73
	v_fmac_f32_e32 v90, 0x3e38aa3b, v74
	v_fmac_f32_e32 v91, 0x3e38aa3b, v75
	v_fmac_f32_e32 v92, 0x3e38aa3b, v76
	v_fmac_f32_e32 v93, 0x3e38aa3b, v77
	v_fmac_f32_e32 v94, 0x3e38aa3b, v78
	v_fmac_f32_e32 v95, 0x3e38aa3b, v79
	v_fmac_f32_e32 v96, 0x3e38aa3b, v48
	v_fmac_f32_e32 v97, 0x3e38aa3b, v49
	v_fmac_f32_e32 v98, 0x3e38aa3b, v50
	v_fmac_f32_e32 v99, 0x3e38aa3b, v51
	s_nop 7
	v_fmac_f32_e32 v100, 0x3e38aa3b, v80
	v_fmac_f32_e32 v101, 0x3e38aa3b, v81
	v_fmac_f32_e32 v102, 0x3e38aa3b, v82
	v_fmac_f32_e32 v103, 0x3e38aa3b, v83
	v_max3_f32 v196, v88, s15, v89
	v_max3_f32 v196, v196, v90, v91
	v_max3_f32 v196, v196, v92, v93
	v_max3_f32 v196, v196, v94, v95
	v_max3_f32 v196, v196, v96, v97
	v_max3_f32 v196, v196, v98, v99
	v_max3_f32 v196, v196, v100, v101
	v_max3_f32 v196, v196, v102, v103
	ds_bpermute_b32 v197, v45, v196
	s_waitcnt lgkmcnt(0)
	v_max_f32_e32 v197, v197, v197
	v_max_f32_e32 v197, v196, v197
	ds_bpermute_b32 v47, v46, v197
	s_waitcnt lgkmcnt(0)
	v_max3_f32 v47, v70, v197, v47
	ds_read_b64_tr_b16 v[164:165], v69 offset:26624
	ds_read_b64_tr_b16 v[166:167], v69 offset:31232
	ds_read_b64_tr_b16 v[168:169], v69 offset:26656
	ds_read_b64_tr_b16 v[170:171], v69 offset:31264
	ds_read_b64_tr_b16 v[172:173], v69 offset:26688
	ds_read_b64_tr_b16 v[174:175], v69 offset:31296
	ds_read_b64_tr_b16 v[176:177], v69 offset:26720
	ds_read_b64_tr_b16 v[178:179], v69 offset:31328
	v_sub_f32_e32 v70, v70, v47
	v_sub_f32_e32 v88, v88, v47
	v_sub_f32_e32 v89, v89, v47
	v_sub_f32_e32 v90, v90, v47
	v_sub_f32_e32 v91, v91, v47
	v_sub_f32_e32 v92, v92, v47
	v_sub_f32_e32 v93, v93, v47
	v_sub_f32_e32 v94, v94, v47
	v_sub_f32_e32 v95, v95, v47
	v_sub_f32_e32 v96, v96, v47
	v_sub_f32_e32 v97, v97, v47
	v_sub_f32_e32 v98, v98, v47
	v_sub_f32_e32 v99, v99, v47
	v_sub_f32_e32 v100, v100, v47
	v_sub_f32_e32 v101, v101, v47
	v_sub_f32_e32 v102, v102, v47
	v_sub_f32_e32 v103, v103, v47
	v_exp_f32_e32 v44, v70
	v_exp_f32_e32 v88, v88
	v_exp_f32_e32 v89, v89
	v_exp_f32_e32 v90, v90
	v_exp_f32_e32 v91, v91
	v_exp_f32_e32 v92, v92
	v_exp_f32_e32 v93, v93
	v_exp_f32_e32 v94, v94
	v_exp_f32_e32 v95, v95
	v_exp_f32_e32 v96, v96
	v_exp_f32_e32 v97, v97
	v_exp_f32_e32 v98, v98
	v_exp_f32_e32 v99, v99
	v_exp_f32_e32 v100, v100
	v_exp_f32_e32 v101, v101
	v_exp_f32_e32 v102, v102
	v_exp_f32_e32 v103, v103
	v_pk_mul_f32 v[28:29], v[28:29], v[44:45] op_sel_hi:[1,0]
	v_pk_mul_f32 v[30:31], v[30:31], v[44:45] op_sel_hi:[1,0]
	v_pk_mul_f32 v[32:33], v[32:33], v[44:45] op_sel_hi:[1,0]
	v_pk_mul_f32 v[34:35], v[34:35], v[44:45] op_sel_hi:[1,0]
	v_pk_mul_f32 v[36:37], v[36:37], v[44:45] op_sel_hi:[1,0]
	v_pk_mul_f32 v[38:39], v[38:39], v[44:45] op_sel_hi:[1,0]
	v_pk_mul_f32 v[40:41], v[40:41], v[44:45] op_sel_hi:[1,0]
	v_pk_mul_f32 v[42:43], v[42:43], v[44:45] op_sel_hi:[1,0]
	v_add_f32_e32 v48, 0, v88
	v_add_f32_e32 v48, v89, v48
	v_add_f32_e32 v48, v90, v48
	v_add_f32_e32 v48, v91, v48
	v_add_f32_e32 v48, v92, v48
	v_add_f32_e32 v48, v93, v48
	v_add_f32_e32 v48, v94, v48
	v_add_f32_e32 v48, v95, v48
	v_add_f32_e32 v48, v96, v48
	v_add_f32_e32 v48, v97, v48
	v_add_f32_e32 v48, v98, v48
	v_add_f32_e32 v48, v99, v48
	v_add_f32_e32 v48, v100, v48
	v_add_f32_e32 v48, v101, v48
	v_add_f32_e32 v48, v102, v48
	v_add_f32_e32 v48, v103, v48
	v_fmac_f32_e32 v48, v68, v44
	v_cvt_pk_bf16_f32 v198, v88, v89
	v_cvt_pk_bf16_f32 v199, v90, v91
	v_cvt_pk_bf16_f32 v200, v92, v93
	v_cvt_pk_bf16_f32 v201, v94, v95
	v_cvt_pk_bf16_f32 v214, v96, v97
	v_cvt_pk_bf16_f32 v215, v98, v99
	v_cvt_pk_bf16_f32 v216, v100, v101
	v_cvt_pk_bf16_f32 v217, v102, v103
	s_add_i32 s15, s7, 1
	s_waitcnt lgkmcnt(8)
	v_mfma_f32_16x16x32_bf16 v[28:31], v[148:151], v[198:201], v[28:31]
	v_mfma_f32_16x16x32_bf16 v[32:35], v[152:155], v[198:201], v[32:35]
	v_mfma_f32_16x16x32_bf16 v[36:39], v[156:159], v[198:201], v[36:39]
	v_mfma_f32_16x16x32_bf16 v[40:43], v[160:163], v[198:201], v[40:43]
	s_waitcnt lgkmcnt(0)
	v_mfma_f32_16x16x32_bf16 v[28:31], v[164:167], v[214:217], v[28:31]
	v_mfma_f32_16x16x32_bf16 v[32:35], v[168:171], v[214:217], v[32:35]
	v_mfma_f32_16x16x32_bf16 v[36:39], v[172:175], v[214:217], v[36:39]
	v_mfma_f32_16x16x32_bf16 v[40:43], v[176:179], v[214:217], v[40:43]
	s_cmp_lt_u32 s7, 8
	s_cbranch_scc0 .LBB0_425
	v_mov_b32_e32 v70, v47
	v_mov_b32_e32 v68, v48
	s_mov_b32 s7, s15
	s_branch .LBB0_410
.Lattn_far_b:
	ds_read_b32 v88, v63 offset:1276
	s_branch .Lattn_join_b
